# LN1 no longer writes the fp32 copy of h1 (row mean/rstd kept in two VGPRs per wave); the PEER v-sweep, its only reader, normalises the pre-norm value it loads with the same operations
# speedup vs baseline: 1.0070x; 1.0070x over previous
.LBB0_1029:
	v_mov_b32_e32 v128, v176
	s_waitcnt vmcnt(0) lgkmcnt(0)
	s_barrier
	s_nop 4
	v_cvt_pk_bf16_f32 v80, v80, v81
	v_and_b32_e32 v129, 0xc0, v128
	v_and_b32_e32 v130, 31, v128
	v_lshrrev_b32_e32 v131, 1, v128
	v_lshrrev_b32_e32 v128, 2, v128
	v_and_b32_e32 v128, 8, v128
	v_and_or_b32 v130, v131, s93, v130
	v_lshl_or_b32 v128, v129, 1, v128
	v_mad_u64_u32 v[128:129], s[66:67], v130, s0, v[128:129]
	v_cvt_pk_bf16_f32 v81, v82, v83
	v_cvt_pk_bf16_f32 v82, v84, v85
	v_cvt_pk_bf16_f32 v83, v86, v87
	v_add_u32_e32 v84, 0x4000, v128
	v_cvt_pk_bf16_f32 v48, v48, v49
	v_cvt_pk_bf16_f32 v49, v50, v51
	v_cvt_pk_bf16_f32 v50, v52, v53
	v_cvt_pk_bf16_f32 v51, v54, v55
	v_add_u32_e32 v52, 0x8000, v128
	v_cvt_pk_bf16_f32 v16, v16, v17
	v_cvt_pk_bf16_f32 v17, v18, v19
	v_cvt_pk_bf16_f32 v18, v20, v21
	v_cvt_pk_bf16_f32 v19, v22, v23
	ds_write2_b64 v128, v[80:81], v[82:83] offset0:8 offset1:10
	v_cvt_pk_bf16_f32 v80, v88, v89
	v_cvt_pk_bf16_f32 v81, v90, v91
	v_cvt_pk_bf16_f32 v82, v92, v93
	v_cvt_pk_bf16_f32 v83, v94, v95
	ds_write2_b64 v84, v[48:49], v[50:51] offset0:72 offset1:74
	v_cvt_pk_bf16_f32 v48, v56, v57
	v_cvt_pk_bf16_f32 v49, v58, v59
	v_cvt_pk_bf16_f32 v50, v60, v61
	v_cvt_pk_bf16_f32 v51, v62, v63
	ds_write2_b64 v52, v[16:17], v[18:19] offset0:136 offset1:138
	v_cvt_pk_bf16_f32 v16, v24, v25
	v_cvt_pk_bf16_f32 v17, v26, v27
	v_cvt_pk_bf16_f32 v18, v28, v29
	v_cvt_pk_bf16_f32 v19, v30, v31
	v_add_u32_e32 v20, 0xc000, v128
	v_cvt_pk_bf16_f32 v0, v0, v1
	v_cvt_pk_bf16_f32 v1, v2, v3
	v_cvt_pk_bf16_f32 v2, v4, v5
	v_cvt_pk_bf16_f32 v3, v6, v7
	v_cvt_pk_bf16_f32 v112, v112, v113
	v_cvt_pk_bf16_f32 v113, v114, v115
	v_cvt_pk_bf16_f32 v114, v116, v117
	v_cvt_pk_bf16_f32 v115, v118, v119
	ds_write2_b64 v128, v[80:81], v[82:83] offset0:12 offset1:14
	v_cvt_pk_bf16_f32 v80, v96, v97
	v_cvt_pk_bf16_f32 v81, v98, v99
	v_cvt_pk_bf16_f32 v82, v100, v101
	v_cvt_pk_bf16_f32 v83, v102, v103
	ds_write2_b64 v84, v[48:49], v[50:51] offset0:76 offset1:78
	v_cvt_pk_bf16_f32 v48, v64, v65
	v_cvt_pk_bf16_f32 v49, v66, v67
	v_cvt_pk_bf16_f32 v50, v68, v69
	v_cvt_pk_bf16_f32 v51, v70, v71
	ds_write2_b64 v52, v[16:17], v[18:19] offset0:140 offset1:142
	v_cvt_pk_bf16_f32 v16, v32, v33
	v_cvt_pk_bf16_f32 v17, v34, v35
	v_cvt_pk_bf16_f32 v18, v36, v37
	v_cvt_pk_bf16_f32 v19, v38, v39
	ds_write2_b64 v20, v[0:1], v[2:3] offset0:200 offset1:202
	v_cvt_pk_bf16_f32 v0, v8, v9
	v_cvt_pk_bf16_f32 v1, v10, v11
	v_cvt_pk_bf16_f32 v2, v12, v13
	v_cvt_pk_bf16_f32 v3, v14, v15
	ds_write2_b64 v128, v[112:113], v[114:115] offset1:2
	v_cvt_pk_bf16_f32 v112, v120, v121
	v_cvt_pk_bf16_f32 v113, v122, v123
	v_cvt_pk_bf16_f32 v114, v124, v125
	v_cvt_pk_bf16_f32 v115, v126, v127
	ds_write2_b64 v84, v[80:81], v[82:83] offset0:64 offset1:66
	v_cvt_pk_bf16_f32 v80, v104, v105
	v_cvt_pk_bf16_f32 v81, v106, v107
	v_cvt_pk_bf16_f32 v82, v108, v109
	v_cvt_pk_bf16_f32 v83, v110, v111
	ds_write2_b64 v52, v[48:49], v[50:51] offset0:128 offset1:130
	v_cvt_pk_bf16_f32 v48, v72, v73
	v_cvt_pk_bf16_f32 v49, v74, v75
	v_cvt_pk_bf16_f32 v50, v76, v77
	v_cvt_pk_bf16_f32 v51, v78, v79
	ds_write2_b64 v20, v[16:17], v[18:19] offset0:192 offset1:194
	v_cvt_pk_bf16_f32 v16, v40, v41
	v_cvt_pk_bf16_f32 v17, v42, v43
	v_cvt_pk_bf16_f32 v18, v44, v45
	v_cvt_pk_bf16_f32 v19, v46, v47
	ds_write2_b64 v20, v[0:1], v[2:3] offset0:204 offset1:206
	v_mov_b32_e32 v1, v176
	ds_write2_b64 v128, v[112:113], v[114:115] offset0:4 offset1:6
	ds_write2_b64 v84, v[80:81], v[82:83] offset0:68 offset1:70
	ds_write2_b64 v52, v[48:49], v[50:51] offset0:132 offset1:134
	ds_write2_b64 v20, v[16:17], v[18:19] offset0:196 offset1:198
	s_waitcnt lgkmcnt(0)
	s_barrier
	v_mov_b32_e32 v1, v176
	s_mov_b32 s98, 0xffff0000
	v_lshlrev_b32_e32 v0, 4, v1
	v_and_b32_e32 v0, 0x1f0, v0
	v_lshrrev_b32_e32 v2, 5, v1
	v_mov_b32_e32 v6, 0x210
	v_mad_u32_u24 v4, v2, v6, v0
	v_add_u32_e32 v5, 0x10800, v4
	v_lshlrev_b32_e32 v6, 3, v1
	v_and_b32_e32 v6, 0xf8, v6
	v_lshl_or_b32 v132, s70, 8, v6
	v_lshlrev_b32_e32 v3, 1, v132
	v_lshl_add_u32 v3, v2, 11, v3
	v_lshlrev_b32_e32 v20, 2, v132
	v_lshl_add_u32 v20, v2, 12, v20
	v_add_u32_e32 v6, 0x0, v3
	global_load_dwordx4 v[32:35], v6, s[52:53]
	ds_read_b128 v[96:99], v4
	v_add_u32_e32 v6, 0x8000, v3
	global_load_dwordx4 v[36:39], v6, s[52:53]
	ds_read_b128 v[100:103], v4 offset:8448
	v_add_u32_e32 v6, 0x10000, v3
	global_load_dwordx4 v[40:43], v6, s[52:53]
	ds_read_b128 v[104:107], v4 offset:16896
	v_add_u32_e32 v6, 0x18000, v3
	global_load_dwordx4 v[44:47], v6, s[52:53]
	ds_read_b128 v[108:111], v4 offset:25344
	v_add_u32_e32 v6, 0x20000, v3
	global_load_dwordx4 v[48:51], v6, s[52:53]
	ds_read_b128 v[112:115], v4 offset:33792
	v_add_u32_e32 v6, 0x28000, v3
	global_load_dwordx4 v[52:55], v6, s[52:53]
	ds_read_b128 v[116:119], v4 offset:42240
	v_add_u32_e32 v6, 0x30000, v3
	global_load_dwordx4 v[56:59], v6, s[52:53]
	ds_read_b128 v[120:123], v4 offset:50688
	v_add_u32_e32 v6, 0x38000, v3
	global_load_dwordx4 v[60:63], v6, s[52:53]
	ds_read_b128 v[124:127], v4 offset:59136
	v_add_u32_e32 v6, 0x40000, v3
	global_load_dwordx4 v[64:67], v6, s[52:53]
	v_add_u32_e32 v6, 0x48000, v3
	global_load_dwordx4 v[68:71], v6, s[52:53]
	v_add_u32_e32 v6, 0x50000, v3
	global_load_dwordx4 v[72:75], v6, s[52:53]
	v_add_u32_e32 v6, 0x58000, v3
	global_load_dwordx4 v[76:79], v6, s[52:53]
	v_add_u32_e32 v6, 0x60000, v3
	global_load_dwordx4 v[80:83], v6, s[52:53]
	v_add_u32_e32 v6, 0x68000, v3
	global_load_dwordx4 v[84:87], v6, s[52:53]
	v_add_u32_e32 v6, 0x70000, v3
	global_load_dwordx4 v[88:91], v6, s[52:53]
	v_add_u32_e32 v6, 0x78000, v3
	global_load_dwordx4 v[92:95], v6, s[52:53]
	s_waitcnt vmcnt(15) lgkmcnt(7)
	v_lshlrev_b32_e32 v8, 16, v32
	v_and_b32_e32 v9, s98, v32
	v_lshlrev_b32_e32 v10, 16, v33
	v_and_b32_e32 v11, s98, v33
	v_lshlrev_b32_e32 v12, 16, v34
	v_and_b32_e32 v13, s98, v34
	v_lshlrev_b32_e32 v14, 16, v35
	v_and_b32_e32 v15, s98, v35
	v_lshlrev_b32_e32 v22, 16, v96
	v_and_b32_e32 v23, s98, v96
	v_lshlrev_b32_e32 v24, 16, v97
	v_and_b32_e32 v25, s98, v97
	v_lshlrev_b32_e32 v26, 16, v98
	v_and_b32_e32 v27, s98, v98
	v_lshlrev_b32_e32 v28, 16, v99
	v_and_b32_e32 v29, s98, v99
	v_pk_fma_f32 v[22:23], v[8:9], s[38:39], v[22:23] op_sel_hi:[1,0,1]
	v_pk_fma_f32 v[24:25], v[10:11], s[38:39], v[24:25] op_sel_hi:[1,0,1]
	v_pk_fma_f32 v[26:27], v[12:13], s[38:39], v[26:27] op_sel_hi:[1,0,1]
	v_pk_fma_f32 v[28:29], v[14:15], s[38:39], v[28:29] op_sel_hi:[1,0,1]
	ds_read_b128 v[96:99], v5
	v_add_u32_e32 v7, 0x0, v20
	global_store_dwordx4 v7, v[22:25], s[64:65]
	global_store_dwordx4 v7, v[26:29], s[64:65] offset:16
	s_waitcnt vmcnt(16) lgkmcnt(7)
	v_lshlrev_b32_e32 v8, 16, v36
	v_and_b32_e32 v9, s98, v36
	v_lshlrev_b32_e32 v10, 16, v37
	v_and_b32_e32 v11, s98, v37
	v_lshlrev_b32_e32 v12, 16, v38
	v_and_b32_e32 v13, s98, v38
	v_lshlrev_b32_e32 v14, 16, v39
	v_and_b32_e32 v15, s98, v39
	v_lshlrev_b32_e32 v22, 16, v100
	v_and_b32_e32 v23, s98, v100
	v_lshlrev_b32_e32 v24, 16, v101
	v_and_b32_e32 v25, s98, v101
	v_lshlrev_b32_e32 v26, 16, v102
	v_and_b32_e32 v27, s98, v102
	v_lshlrev_b32_e32 v28, 16, v103
	v_and_b32_e32 v29, s98, v103
	v_pk_fma_f32 v[22:23], v[8:9], s[38:39], v[22:23] op_sel_hi:[1,0,1]
	v_pk_fma_f32 v[24:25], v[10:11], s[38:39], v[24:25] op_sel_hi:[1,0,1]
	v_pk_fma_f32 v[26:27], v[12:13], s[38:39], v[26:27] op_sel_hi:[1,0,1]
	v_pk_fma_f32 v[28:29], v[14:15], s[38:39], v[28:29] op_sel_hi:[1,0,1]
	ds_read_b128 v[100:103], v5 offset:8448
	v_add_u32_e32 v7, 0x10000, v20
	global_store_dwordx4 v7, v[22:25], s[64:65]
	global_store_dwordx4 v7, v[26:29], s[64:65] offset:16
	s_waitcnt vmcnt(17) lgkmcnt(7)
	v_lshlrev_b32_e32 v8, 16, v40
	v_and_b32_e32 v9, s98, v40
	v_lshlrev_b32_e32 v10, 16, v41
	v_and_b32_e32 v11, s98, v41
	v_lshlrev_b32_e32 v12, 16, v42
	v_and_b32_e32 v13, s98, v42
	v_lshlrev_b32_e32 v14, 16, v43
	v_and_b32_e32 v15, s98, v43
	v_lshlrev_b32_e32 v22, 16, v104
	v_and_b32_e32 v23, s98, v104
	v_lshlrev_b32_e32 v24, 16, v105
	v_and_b32_e32 v25, s98, v105
	v_lshlrev_b32_e32 v26, 16, v106
	v_and_b32_e32 v27, s98, v106
	v_lshlrev_b32_e32 v28, 16, v107
	v_and_b32_e32 v29, s98, v107
	v_pk_fma_f32 v[22:23], v[8:9], s[38:39], v[22:23] op_sel_hi:[1,0,1]
	v_pk_fma_f32 v[24:25], v[10:11], s[38:39], v[24:25] op_sel_hi:[1,0,1]
	v_pk_fma_f32 v[26:27], v[12:13], s[38:39], v[26:27] op_sel_hi:[1,0,1]
	v_pk_fma_f32 v[28:29], v[14:15], s[38:39], v[28:29] op_sel_hi:[1,0,1]
	ds_read_b128 v[104:107], v5 offset:16896
	v_add_u32_e32 v7, 0x20000, v20
	global_store_dwordx4 v7, v[22:25], s[64:65]
	global_store_dwordx4 v7, v[26:29], s[64:65] offset:16
	s_waitcnt vmcnt(18) lgkmcnt(7)
	v_lshlrev_b32_e32 v8, 16, v44
	v_and_b32_e32 v9, s98, v44
	v_lshlrev_b32_e32 v10, 16, v45
	v_and_b32_e32 v11, s98, v45
	v_lshlrev_b32_e32 v12, 16, v46
	v_and_b32_e32 v13, s98, v46
	v_lshlrev_b32_e32 v14, 16, v47
	v_and_b32_e32 v15, s98, v47
	v_lshlrev_b32_e32 v22, 16, v108
	v_and_b32_e32 v23, s98, v108
	v_lshlrev_b32_e32 v24, 16, v109
	v_and_b32_e32 v25, s98, v109
	v_lshlrev_b32_e32 v26, 16, v110
	v_and_b32_e32 v27, s98, v110
	v_lshlrev_b32_e32 v28, 16, v111
	v_and_b32_e32 v29, s98, v111
	v_pk_fma_f32 v[22:23], v[8:9], s[38:39], v[22:23] op_sel_hi:[1,0,1]
	v_pk_fma_f32 v[24:25], v[10:11], s[38:39], v[24:25] op_sel_hi:[1,0,1]
	v_pk_fma_f32 v[26:27], v[12:13], s[38:39], v[26:27] op_sel_hi:[1,0,1]
	v_pk_fma_f32 v[28:29], v[14:15], s[38:39], v[28:29] op_sel_hi:[1,0,1]
	ds_read_b128 v[108:111], v5 offset:25344
	v_add_u32_e32 v7, 0x30000, v20
	global_store_dwordx4 v7, v[22:25], s[64:65]
	global_store_dwordx4 v7, v[26:29], s[64:65] offset:16
	s_waitcnt vmcnt(19) lgkmcnt(7)
	v_lshlrev_b32_e32 v8, 16, v48
	v_and_b32_e32 v9, s98, v48
	v_lshlrev_b32_e32 v10, 16, v49
	v_and_b32_e32 v11, s98, v49
	v_lshlrev_b32_e32 v12, 16, v50
	v_and_b32_e32 v13, s98, v50
	v_lshlrev_b32_e32 v14, 16, v51
	v_and_b32_e32 v15, s98, v51
	v_lshlrev_b32_e32 v22, 16, v112
	v_and_b32_e32 v23, s98, v112
	v_lshlrev_b32_e32 v24, 16, v113
	v_and_b32_e32 v25, s98, v113
	v_lshlrev_b32_e32 v26, 16, v114
	v_and_b32_e32 v27, s98, v114
	v_lshlrev_b32_e32 v28, 16, v115
	v_and_b32_e32 v29, s98, v115
	v_pk_fma_f32 v[22:23], v[8:9], s[38:39], v[22:23] op_sel_hi:[1,0,1]
	v_pk_fma_f32 v[24:25], v[10:11], s[38:39], v[24:25] op_sel_hi:[1,0,1]
	v_pk_fma_f32 v[26:27], v[12:13], s[38:39], v[26:27] op_sel_hi:[1,0,1]
	v_pk_fma_f32 v[28:29], v[14:15], s[38:39], v[28:29] op_sel_hi:[1,0,1]
	ds_read_b128 v[112:115], v5 offset:33792
	v_add_u32_e32 v7, 0x40000, v20
	global_store_dwordx4 v7, v[22:25], s[64:65]
	global_store_dwordx4 v7, v[26:29], s[64:65] offset:16
	s_waitcnt vmcnt(20) lgkmcnt(7)
	v_lshlrev_b32_e32 v8, 16, v52
	v_and_b32_e32 v9, s98, v52
	v_lshlrev_b32_e32 v10, 16, v53
	v_and_b32_e32 v11, s98, v53
	v_lshlrev_b32_e32 v12, 16, v54
	v_and_b32_e32 v13, s98, v54
	v_lshlrev_b32_e32 v14, 16, v55
	v_and_b32_e32 v15, s98, v55
	v_lshlrev_b32_e32 v22, 16, v116
	v_and_b32_e32 v23, s98, v116
	v_lshlrev_b32_e32 v24, 16, v117
	v_and_b32_e32 v25, s98, v117
	v_lshlrev_b32_e32 v26, 16, v118
	v_and_b32_e32 v27, s98, v118
	v_lshlrev_b32_e32 v28, 16, v119
	v_and_b32_e32 v29, s98, v119
	v_pk_fma_f32 v[22:23], v[8:9], s[38:39], v[22:23] op_sel_hi:[1,0,1]
	v_pk_fma_f32 v[24:25], v[10:11], s[38:39], v[24:25] op_sel_hi:[1,0,1]
	v_pk_fma_f32 v[26:27], v[12:13], s[38:39], v[26:27] op_sel_hi:[1,0,1]
	v_pk_fma_f32 v[28:29], v[14:15], s[38:39], v[28:29] op_sel_hi:[1,0,1]
	ds_read_b128 v[116:119], v5 offset:42240
	v_add_u32_e32 v7, 0x50000, v20
	global_store_dwordx4 v7, v[22:25], s[64:65]
	global_store_dwordx4 v7, v[26:29], s[64:65] offset:16
	s_waitcnt vmcnt(21) lgkmcnt(7)
	v_lshlrev_b32_e32 v8, 16, v56
	v_and_b32_e32 v9, s98, v56
	v_lshlrev_b32_e32 v10, 16, v57
	v_and_b32_e32 v11, s98, v57
	v_lshlrev_b32_e32 v12, 16, v58
	v_and_b32_e32 v13, s98, v58
	v_lshlrev_b32_e32 v14, 16, v59
	v_and_b32_e32 v15, s98, v59
	v_lshlrev_b32_e32 v22, 16, v120
	v_and_b32_e32 v23, s98, v120
	v_lshlrev_b32_e32 v24, 16, v121
	v_and_b32_e32 v25, s98, v121
	v_lshlrev_b32_e32 v26, 16, v122
	v_and_b32_e32 v27, s98, v122
	v_lshlrev_b32_e32 v28, 16, v123
	v_and_b32_e32 v29, s98, v123
	v_pk_fma_f32 v[22:23], v[8:9], s[38:39], v[22:23] op_sel_hi:[1,0,1]
	v_pk_fma_f32 v[24:25], v[10:11], s[38:39], v[24:25] op_sel_hi:[1,0,1]
	v_pk_fma_f32 v[26:27], v[12:13], s[38:39], v[26:27] op_sel_hi:[1,0,1]
	v_pk_fma_f32 v[28:29], v[14:15], s[38:39], v[28:29] op_sel_hi:[1,0,1]
	ds_read_b128 v[120:123], v5 offset:50688
	v_add_u32_e32 v7, 0x60000, v20
	global_store_dwordx4 v7, v[22:25], s[64:65]
	global_store_dwordx4 v7, v[26:29], s[64:65] offset:16
	s_waitcnt vmcnt(22) lgkmcnt(7)
	v_lshlrev_b32_e32 v8, 16, v60
	v_and_b32_e32 v9, s98, v60
	v_lshlrev_b32_e32 v10, 16, v61
	v_and_b32_e32 v11, s98, v61
	v_lshlrev_b32_e32 v12, 16, v62
	v_and_b32_e32 v13, s98, v62
	v_lshlrev_b32_e32 v14, 16, v63
	v_and_b32_e32 v15, s98, v63
	v_lshlrev_b32_e32 v22, 16, v124
	v_and_b32_e32 v23, s98, v124
	v_lshlrev_b32_e32 v24, 16, v125
	v_and_b32_e32 v25, s98, v125
	v_lshlrev_b32_e32 v26, 16, v126
	v_and_b32_e32 v27, s98, v126
	v_lshlrev_b32_e32 v28, 16, v127
	v_and_b32_e32 v29, s98, v127
	v_pk_fma_f32 v[22:23], v[8:9], s[38:39], v[22:23] op_sel_hi:[1,0,1]
	v_pk_fma_f32 v[24:25], v[10:11], s[38:39], v[24:25] op_sel_hi:[1,0,1]
	v_pk_fma_f32 v[26:27], v[12:13], s[38:39], v[26:27] op_sel_hi:[1,0,1]
	v_pk_fma_f32 v[28:29], v[14:15], s[38:39], v[28:29] op_sel_hi:[1,0,1]
	ds_read_b128 v[124:127], v5 offset:59136
	v_add_u32_e32 v7, 0x70000, v20
	global_store_dwordx4 v7, v[22:25], s[64:65]
	global_store_dwordx4 v7, v[26:29], s[64:65] offset:16
	s_waitcnt vmcnt(23) lgkmcnt(7)
	v_lshlrev_b32_e32 v8, 16, v64
	v_and_b32_e32 v9, s98, v64
	v_lshlrev_b32_e32 v10, 16, v65
	v_and_b32_e32 v11, s98, v65
	v_lshlrev_b32_e32 v12, 16, v66
	v_and_b32_e32 v13, s98, v66
	v_lshlrev_b32_e32 v14, 16, v67
	v_and_b32_e32 v15, s98, v67
	v_lshlrev_b32_e32 v22, 16, v96
	v_and_b32_e32 v23, s98, v96
	v_lshlrev_b32_e32 v24, 16, v97
	v_and_b32_e32 v25, s98, v97
	v_lshlrev_b32_e32 v26, 16, v98
	v_and_b32_e32 v27, s98, v98
	v_lshlrev_b32_e32 v28, 16, v99
	v_and_b32_e32 v29, s98, v99
	v_pk_fma_f32 v[22:23], v[8:9], s[38:39], v[22:23] op_sel_hi:[1,0,1]
	v_pk_fma_f32 v[24:25], v[10:11], s[38:39], v[24:25] op_sel_hi:[1,0,1]
	v_pk_fma_f32 v[26:27], v[12:13], s[38:39], v[26:27] op_sel_hi:[1,0,1]
	v_pk_fma_f32 v[28:29], v[14:15], s[38:39], v[28:29] op_sel_hi:[1,0,1]
	v_add_u32_e32 v7, 0x80000, v20
	global_store_dwordx4 v7, v[22:25], s[64:65]
	global_store_dwordx4 v7, v[26:29], s[64:65] offset:16
	s_waitcnt vmcnt(24) lgkmcnt(6)
	v_lshlrev_b32_e32 v8, 16, v68
	v_and_b32_e32 v9, s98, v68
	v_lshlrev_b32_e32 v10, 16, v69
	v_and_b32_e32 v11, s98, v69
	v_lshlrev_b32_e32 v12, 16, v70
	v_and_b32_e32 v13, s98, v70
	v_lshlrev_b32_e32 v14, 16, v71
	v_and_b32_e32 v15, s98, v71
	v_lshlrev_b32_e32 v22, 16, v100
	v_and_b32_e32 v23, s98, v100
	v_lshlrev_b32_e32 v24, 16, v101
	v_and_b32_e32 v25, s98, v101
	v_lshlrev_b32_e32 v26, 16, v102
	v_and_b32_e32 v27, s98, v102
	v_lshlrev_b32_e32 v28, 16, v103
	v_and_b32_e32 v29, s98, v103
	v_pk_fma_f32 v[22:23], v[8:9], s[38:39], v[22:23] op_sel_hi:[1,0,1]
	v_pk_fma_f32 v[24:25], v[10:11], s[38:39], v[24:25] op_sel_hi:[1,0,1]
	v_pk_fma_f32 v[26:27], v[12:13], s[38:39], v[26:27] op_sel_hi:[1,0,1]
	v_pk_fma_f32 v[28:29], v[14:15], s[38:39], v[28:29] op_sel_hi:[1,0,1]
	v_add_u32_e32 v7, 0x90000, v20
	global_store_dwordx4 v7, v[22:25], s[64:65]
	global_store_dwordx4 v7, v[26:29], s[64:65] offset:16
	s_waitcnt vmcnt(25) lgkmcnt(5)
	v_lshlrev_b32_e32 v8, 16, v72
	v_and_b32_e32 v9, s98, v72
	v_lshlrev_b32_e32 v10, 16, v73
	v_and_b32_e32 v11, s98, v73
	v_lshlrev_b32_e32 v12, 16, v74
	v_and_b32_e32 v13, s98, v74
	v_lshlrev_b32_e32 v14, 16, v75
	v_and_b32_e32 v15, s98, v75
	v_lshlrev_b32_e32 v22, 16, v104
	v_and_b32_e32 v23, s98, v104
	v_lshlrev_b32_e32 v24, 16, v105
	v_and_b32_e32 v25, s98, v105
	v_lshlrev_b32_e32 v26, 16, v106
	v_and_b32_e32 v27, s98, v106
	v_lshlrev_b32_e32 v28, 16, v107
	v_and_b32_e32 v29, s98, v107
	v_pk_fma_f32 v[22:23], v[8:9], s[38:39], v[22:23] op_sel_hi:[1,0,1]
	v_pk_fma_f32 v[24:25], v[10:11], s[38:39], v[24:25] op_sel_hi:[1,0,1]
	v_pk_fma_f32 v[26:27], v[12:13], s[38:39], v[26:27] op_sel_hi:[1,0,1]
	v_pk_fma_f32 v[28:29], v[14:15], s[38:39], v[28:29] op_sel_hi:[1,0,1]
	v_add_u32_e32 v7, 0xa0000, v20
	global_store_dwordx4 v7, v[22:25], s[64:65]
	global_store_dwordx4 v7, v[26:29], s[64:65] offset:16
	s_waitcnt vmcnt(26) lgkmcnt(4)
	v_lshlrev_b32_e32 v8, 16, v76
	v_and_b32_e32 v9, s98, v76
	v_lshlrev_b32_e32 v10, 16, v77
	v_and_b32_e32 v11, s98, v77
	v_lshlrev_b32_e32 v12, 16, v78
	v_and_b32_e32 v13, s98, v78
	v_lshlrev_b32_e32 v14, 16, v79
	v_and_b32_e32 v15, s98, v79
	v_lshlrev_b32_e32 v22, 16, v108
	v_and_b32_e32 v23, s98, v108
	v_lshlrev_b32_e32 v24, 16, v109
	v_and_b32_e32 v25, s98, v109
	v_lshlrev_b32_e32 v26, 16, v110
	v_and_b32_e32 v27, s98, v110
	v_lshlrev_b32_e32 v28, 16, v111
	v_and_b32_e32 v29, s98, v111
	v_pk_fma_f32 v[22:23], v[8:9], s[38:39], v[22:23] op_sel_hi:[1,0,1]
	v_pk_fma_f32 v[24:25], v[10:11], s[38:39], v[24:25] op_sel_hi:[1,0,1]
	v_pk_fma_f32 v[26:27], v[12:13], s[38:39], v[26:27] op_sel_hi:[1,0,1]
	v_pk_fma_f32 v[28:29], v[14:15], s[38:39], v[28:29] op_sel_hi:[1,0,1]
	v_add_u32_e32 v7, 0xb0000, v20
	global_store_dwordx4 v7, v[22:25], s[64:65]
	global_store_dwordx4 v7, v[26:29], s[64:65] offset:16
	s_waitcnt vmcnt(27) lgkmcnt(3)
	v_lshlrev_b32_e32 v8, 16, v80
	v_and_b32_e32 v9, s98, v80
	v_lshlrev_b32_e32 v10, 16, v81
	v_and_b32_e32 v11, s98, v81
	v_lshlrev_b32_e32 v12, 16, v82
	v_and_b32_e32 v13, s98, v82
	v_lshlrev_b32_e32 v14, 16, v83
	v_and_b32_e32 v15, s98, v83
	v_lshlrev_b32_e32 v22, 16, v112
	v_and_b32_e32 v23, s98, v112
	v_lshlrev_b32_e32 v24, 16, v113
	v_and_b32_e32 v25, s98, v113
	v_lshlrev_b32_e32 v26, 16, v114
	v_and_b32_e32 v27, s98, v114
	v_lshlrev_b32_e32 v28, 16, v115
	v_and_b32_e32 v29, s98, v115
	v_pk_fma_f32 v[22:23], v[8:9], s[38:39], v[22:23] op_sel_hi:[1,0,1]
	v_pk_fma_f32 v[24:25], v[10:11], s[38:39], v[24:25] op_sel_hi:[1,0,1]
	v_pk_fma_f32 v[26:27], v[12:13], s[38:39], v[26:27] op_sel_hi:[1,0,1]
	v_pk_fma_f32 v[28:29], v[14:15], s[38:39], v[28:29] op_sel_hi:[1,0,1]
	v_add_u32_e32 v7, 0xc0000, v20
	global_store_dwordx4 v7, v[22:25], s[64:65]
	global_store_dwordx4 v7, v[26:29], s[64:65] offset:16
	s_waitcnt vmcnt(28) lgkmcnt(2)
	v_lshlrev_b32_e32 v8, 16, v84
	v_and_b32_e32 v9, s98, v84
	v_lshlrev_b32_e32 v10, 16, v85
	v_and_b32_e32 v11, s98, v85
	v_lshlrev_b32_e32 v12, 16, v86
	v_and_b32_e32 v13, s98, v86
	v_lshlrev_b32_e32 v14, 16, v87
	v_and_b32_e32 v15, s98, v87
	v_lshlrev_b32_e32 v22, 16, v116
	v_and_b32_e32 v23, s98, v116
	v_lshlrev_b32_e32 v24, 16, v117
	v_and_b32_e32 v25, s98, v117
	v_lshlrev_b32_e32 v26, 16, v118
	v_and_b32_e32 v27, s98, v118
	v_lshlrev_b32_e32 v28, 16, v119
	v_and_b32_e32 v29, s98, v119
	v_pk_fma_f32 v[22:23], v[8:9], s[38:39], v[22:23] op_sel_hi:[1,0,1]
	v_pk_fma_f32 v[24:25], v[10:11], s[38:39], v[24:25] op_sel_hi:[1,0,1]
	v_pk_fma_f32 v[26:27], v[12:13], s[38:39], v[26:27] op_sel_hi:[1,0,1]
	v_pk_fma_f32 v[28:29], v[14:15], s[38:39], v[28:29] op_sel_hi:[1,0,1]
	v_add_u32_e32 v7, 0xd0000, v20
	global_store_dwordx4 v7, v[22:25], s[64:65]
	global_store_dwordx4 v7, v[26:29], s[64:65] offset:16
	s_waitcnt vmcnt(29) lgkmcnt(1)
	v_lshlrev_b32_e32 v8, 16, v88
	v_and_b32_e32 v9, s98, v88
	v_lshlrev_b32_e32 v10, 16, v89
	v_and_b32_e32 v11, s98, v89
	v_lshlrev_b32_e32 v12, 16, v90
	v_and_b32_e32 v13, s98, v90
	v_lshlrev_b32_e32 v14, 16, v91
	v_and_b32_e32 v15, s98, v91
	v_lshlrev_b32_e32 v22, 16, v120
	v_and_b32_e32 v23, s98, v120
	v_lshlrev_b32_e32 v24, 16, v121
	v_and_b32_e32 v25, s98, v121
	v_lshlrev_b32_e32 v26, 16, v122
	v_and_b32_e32 v27, s98, v122
	v_lshlrev_b32_e32 v28, 16, v123
	v_and_b32_e32 v29, s98, v123
	v_pk_fma_f32 v[22:23], v[8:9], s[38:39], v[22:23] op_sel_hi:[1,0,1]
	v_pk_fma_f32 v[24:25], v[10:11], s[38:39], v[24:25] op_sel_hi:[1,0,1]
	v_pk_fma_f32 v[26:27], v[12:13], s[38:39], v[26:27] op_sel_hi:[1,0,1]
	v_pk_fma_f32 v[28:29], v[14:15], s[38:39], v[28:29] op_sel_hi:[1,0,1]
	v_add_u32_e32 v7, 0xe0000, v20
	global_store_dwordx4 v7, v[22:25], s[64:65]
	global_store_dwordx4 v7, v[26:29], s[64:65] offset:16
	s_waitcnt vmcnt(30) lgkmcnt(0)
	v_lshlrev_b32_e32 v8, 16, v92
	v_and_b32_e32 v9, s98, v92
	v_lshlrev_b32_e32 v10, 16, v93
	v_and_b32_e32 v11, s98, v93
	v_lshlrev_b32_e32 v12, 16, v94
	v_and_b32_e32 v13, s98, v94
	v_lshlrev_b32_e32 v14, 16, v95
	v_and_b32_e32 v15, s98, v95
	v_lshlrev_b32_e32 v22, 16, v124
	v_and_b32_e32 v23, s98, v124
	v_lshlrev_b32_e32 v24, 16, v125
	v_and_b32_e32 v25, s98, v125
	v_lshlrev_b32_e32 v26, 16, v126
	v_and_b32_e32 v27, s98, v126
	v_lshlrev_b32_e32 v28, 16, v127
	v_and_b32_e32 v29, s98, v127
	v_pk_fma_f32 v[22:23], v[8:9], s[38:39], v[22:23] op_sel_hi:[1,0,1]
	v_pk_fma_f32 v[24:25], v[10:11], s[38:39], v[24:25] op_sel_hi:[1,0,1]
	v_pk_fma_f32 v[26:27], v[12:13], s[38:39], v[26:27] op_sel_hi:[1,0,1]
	v_pk_fma_f32 v[28:29], v[14:15], s[38:39], v[28:29] op_sel_hi:[1,0,1]
	v_add_u32_e32 v7, 0xf0000, v20
	global_store_dwordx4 v7, v[22:25], s[64:65]
	global_store_dwordx4 v7, v[26:29], s[64:65] offset:16
	s_movk_i32 s66, 0x2000
	s_add_i32 s70, s70, 1
	s_add_u32 s50, s50, 0x80000
	s_addc_u32 s51, s51, 0
	s_cmp_eq_u32 s70, 4
	s_cbranch_scc0 .LBB0_1023
	s_lshl_b64 s[52:53], s[8:9], 12
	s_mov_b64 s[50:51], 0
	s_barrier
	s_add_u32 s3, s96, s50
	s_addc_u32 s16, s97, s51
	v_mov_b32_e32 v26, v176
	s_add_u32 s3, s3, s62
	v_ashrrev_i32_e32 v0, 1, v26
	s_addc_u32 s16, s16, s63
	v_and_b32_e32 v16, 0xffffffe0, v0
	s_add_u32 s54, s3, 0x18000000
	v_ashrrev_i32_e32 v17, 31, v16
	v_lshlrev_b32_e32 v2, 2, v26
	s_addc_u32 s55, s16, 0
	v_lshlrev_b64 v[24:25], 12, v[16:17]
	v_and_b32_e32 v132, 0xfc, v2
	v_lshl_add_u64 v[0:1], s[54:55], 0, v[24:25]
	v_lshlrev_b32_e32 v22, 2, v132
	v_mov_b32_e32 v23, v133
	v_lshl_add_u64 v[12:13], v[0:1], 0, v[22:23]
	global_load_dwordx4 v[0:3], v[12:13], off
	global_load_dwordx4 v[4:7], v[12:13], off offset:1024
	global_load_dwordx4 v[8:11], v[12:13], off offset:2048
	s_nop 0
	global_load_dwordx4 v[12:15], v[12:13], off offset:3072
	v_xor_b32_e32 v20, 16, v171
	v_and_b32_e32 v30, 63, v26
	v_lshlrev_b64 v[26:27], 10, v[16:17]
	v_cmp_lt_i32_e32 vcc, v20, v178
	v_lshl_add_u64 v[26:27], s[94:95], 0, v[26:27]
	v_lshlrev_b64 v[28:29], 11, v[16:17]
	v_cndmask_b32_e32 v20, v171, v20, vcc
	v_cmp_lt_i32_e32 vcc, v177, v178
	v_readlane_b32 s60, v255, 6
	v_lshl_add_u64 v[24:25], s[52:53], 0, v[24:25]
	v_lshl_add_u64 v[26:27], v[26:27], 0, v[132:133]
	v_lshl_add_u64 v[28:29], s[46:47], 0, v[28:29]
	v_lshlrev_b32_e32 v132, 3, v30
	v_lshlrev_b32_e32 v36, 2, v20
	v_cndmask_b32_e32 v20, v171, v177, vcc
	v_readlane_b32 s64, v255, 10
	v_readlane_b32 s65, v255, 11
	v_readlane_b32 s66, v255, 12
	v_readlane_b32 s67, v255, 13
	v_lshl_or_b32 v24, v30, 4, v24
	v_lshl_add_u64 v[28:29], v[28:29], 0, v[132:133]
	v_lshl_add_u64 v[18:19], s[54:55], 0, v[22:23]
	s_mov_b32 s3, 0
	v_lshlrev_b32_e32 v141, 2, v20
	v_lshl_add_u64 v[20:21], s[64:65], 0, v[22:23]
	v_lshl_add_u64 v[22:23], s[66:67], 0, v[22:23]
	v_lshl_add_u64 v[24:25], s[10:11], 0, v[24:25]
	v_lshl_add_u64 v[26:27], s[12:13], 0, v[26:27]
	v_lshl_add_u64 v[28:29], s[14:15], 0, v[28:29]
	v_readlane_b32 s61, v255, 7
	v_readlane_b32 s62, v255, 8
	v_readlane_b32 s63, v255, 9
	v_readlane_b32 s68, v255, 14
	v_readlane_b32 s69, v255, 15
	v_readlane_b32 s70, v255, 16
	v_readlane_b32 s71, v255, 17
	v_readlane_b32 s72, v255, 18
	v_readlane_b32 s73, v255, 19
	v_readlane_b32 s74, v255, 20
	v_readlane_b32 s75, v255, 21
	v_mbcnt_lo_u32_b32 v254, -1, 0
	v_mbcnt_hi_u32_b32 v254, -1, v254
.LBB0_1033:
	global_load_dwordx4 v[38:41], v[20:21], off
	s_mov_b32 s99, s3
	global_load_dwordx4 v[42:45], v[22:23], off
	s_waitcnt vmcnt(5)
	v_mov_b32_e32 v46, v0
	s_waitcnt vmcnt(4)
	v_mov_b32_e32 v47, v4
	v_mov_b32_e32 v48, v1
	v_mov_b32_e32 v49, v5
	s_cmp_lg_u32 s3, 31
	v_mov_b32_e32 v50, v2
	v_mov_b32_e32 v51, v6
	v_pk_add_f32 v[46:47], v[46:47], v[48:49]
	v_mov_b32_e32 v17, s3
	v_mov_b32_e32 v52, v3
	v_mov_b32_e32 v53, v7
	s_waitcnt vmcnt(3)
	v_mov_b32_e32 v54, v8
	s_waitcnt vmcnt(2)
	v_mov_b32_e32 v55, v12
	v_mov_b32_e32 v56, v9
	v_mov_b32_e32 v57, v13
	s_cselect_b64 vcc, -1, 0
	v_pk_add_f32 v[46:47], v[46:47], v[50:51]
	v_mov_b32_e32 v58, v10
	v_mov_b32_e32 v59, v14
	v_addc_co_u32_e32 v62, vcc, v16, v17, vcc
	v_pk_add_f32 v[48:49], v[54:55], v[56:57]
	v_pk_add_f32 v[46:47], v[46:47], v[52:53]
	v_mov_b32_e32 v60, v11
	v_mov_b32_e32 v61, v15
	v_ashrrev_i32_e32 v63, 31, v62
	v_pk_add_f32 v[48:49], v[48:49], v[58:59]
	v_add_f32_e32 v17, 0, v46
	v_lshlrev_b64 v[50:51], 12, v[62:63]
	v_pk_add_f32 v[62:63], v[48:49], v[60:61]
	v_add_f32_e32 v17, v17, v47
	v_add_f32_e32 v17, v17, v62
	v_add_f32_e32 v17, v17, v63
	s_mov_b32 s16, 0x800000
	v_lshl_add_u64 v[30:31], v[24:25], 0, s[50:51]
	v_add_f32_dpp v17, v17, v17 quad_perm:[1,0,3,2] row_mask:0xf bank_mask:0xf bound_ctrl:1
	v_lshl_add_u64 v[58:59], v[18:19], 0, v[50:51]
	v_mov_b32_e32 v37, 0
	v_add_f32_dpp v17, v17, v17 quad_perm:[2,3,0,1] row_mask:0xf bank_mask:0xf bound_ctrl:1
	global_load_dwordx4 v[46:49], v[58:59], off
	global_load_dwordx4 v[50:53], v[58:59], off offset:1024
	global_load_dwordx4 v[54:57], v[58:59], off offset:2048
	s_nop 0
	global_load_dwordx4 v[58:61], v[58:59], off offset:3072
	v_add_f32_dpp v17, v17, v17 row_ror:4 row_mask:0xf bank_mask:0xf bound_ctrl:1
	v_lshl_add_u64 v[32:33], v[28:29], 0, s[50:51]
	v_lshl_add_u64 v[34:35], v[26:27], 0, s[50:51]
	v_add_f32_dpp v17, v17, v17 row_ror:8 row_mask:0xf bank_mask:0xf bound_ctrl:1
	ds_bpermute_b32 v62, v36, v17
	s_mov_b64 s[52:53], 0x400
	s_mov_b64 s[54:55], 0x800
	s_add_i32 s3, s3, 1
	v_lshl_add_u64 v[24:25], v[24:25], 0, s[4:5]
	s_waitcnt lgkmcnt(0)
	v_add_f32_e32 v17, v17, v62
	ds_bpermute_b32 v62, v141, v17
	v_lshl_add_u64 v[26:27], v[26:27], 0, s[52:53]
	v_lshl_add_u64 v[28:29], v[28:29], 0, s[54:55]
	s_cmp_lg_u32 s3, 32
	s_waitcnt lgkmcnt(0)
	v_add_f32_e32 v17, v17, v62
	v_mul_f32_e32 v62, 0x3a800000, v17
	v_pk_add_f32 v[0:1], v[0:1], v[62:63] op_sel_hi:[1,0] neg_lo:[0,1] neg_hi:[0,1]
	v_pk_add_f32 v[2:3], v[2:3], v[62:63] op_sel_hi:[1,0] neg_lo:[0,1] neg_hi:[0,1]
	v_cmp_eq_u32_e64 s[100:101], s99, v254
	s_nop 1
	v_cndmask_b32_e64 v252, v252, v62, s[100:101]
	v_pk_add_f32 v[64:65], v[4:5], v[62:63] op_sel_hi:[1,0] neg_lo:[0,1] neg_hi:[0,1]
	v_pk_mul_f32 v[4:5], v[0:1], v[0:1]
	v_pk_add_f32 v[66:67], v[6:7], v[62:63] op_sel_hi:[1,0] neg_lo:[0,1] neg_hi:[0,1]
	v_pk_mul_f32 v[6:7], v[2:3], v[2:3]
	v_add_f32_e32 v4, v4, v5
	v_add_f32_e32 v4, v6, v4
	v_pk_add_f32 v[8:9], v[8:9], v[62:63] op_sel_hi:[1,0] neg_lo:[0,1] neg_hi:[0,1]
	v_pk_add_f32 v[10:11], v[10:11], v[62:63] op_sel_hi:[1,0] neg_lo:[0,1] neg_hi:[0,1]
	v_pk_add_f32 v[12:13], v[12:13], v[62:63] op_sel_hi:[1,0] neg_lo:[0,1] neg_hi:[0,1]
	v_pk_add_f32 v[14:15], v[14:15], v[62:63] op_sel_hi:[1,0] neg_lo:[0,1] neg_hi:[0,1]
	v_pk_mul_f32 v[62:63], v[64:65], v[64:65]
	v_add_f32_e32 v4, v7, v4
	v_add_f32_e32 v4, v62, v4
	v_pk_mul_f32 v[68:69], v[66:67], v[66:67]
	v_add_f32_e32 v4, v63, v4
	v_add_f32_e32 v4, v68, v4
	v_pk_mul_f32 v[70:71], v[8:9], v[8:9]
	v_add_f32_e32 v4, v69, v4
	v_add_f32_e32 v4, v70, v4
	v_pk_mul_f32 v[72:73], v[10:11], v[10:11]
	v_add_f32_e32 v4, v71, v4
	v_add_f32_e32 v4, v72, v4
	v_pk_mul_f32 v[74:75], v[12:13], v[12:13]
	v_add_f32_e32 v4, v73, v4
	v_add_f32_e32 v4, v74, v4
	v_pk_mul_f32 v[76:77], v[14:15], v[14:15]
	v_add_f32_e32 v4, v75, v4
	v_add_f32_e32 v4, v76, v4
	v_add_f32_e32 v4, v77, v4
	v_mov_b32_e32 v17, 0
	s_nop 0
	v_add_f32_dpp v4, v4, v4 quad_perm:[1,0,3,2] row_mask:0xf bank_mask:0xf bound_ctrl:1
	s_nop 1
	v_add_f32_dpp v4, v4, v4 quad_perm:[2,3,0,1] row_mask:0xf bank_mask:0xf bound_ctrl:1
	s_nop 1
	v_add_f32_dpp v4, v4, v4 row_ror:4 row_mask:0xf bank_mask:0xf bound_ctrl:1
	s_nop 1
	v_add_f32_dpp v4, v4, v4 row_ror:8 row_mask:0xf bank_mask:0xf bound_ctrl:1
	ds_bpermute_b32 v5, v36, v4
	s_waitcnt lgkmcnt(0)
	v_add_f32_e32 v4, v4, v5
	ds_bpermute_b32 v5, v141, v4
	s_waitcnt lgkmcnt(0)
	v_add_f32_e32 v4, v4, v5
	v_fmamk_f32 v4, v4, 0x3a800000, v138
	v_mul_f32_e32 v5, 0x4b800000, v4
	v_cmp_gt_f32_e32 vcc, s16, v4
	s_nop 1
	v_cndmask_b32_e32 v4, v4, v5, vcc
	v_rsq_f32_e32 v4, v4
	s_nop 0
	v_mul_f32_e32 v5, 0x45800000, v4
	v_cndmask_b32_e32 v62, v4, v5, vcc
	v_pk_mul_f32 v[0:1], v[0:1], v[62:63] op_sel_hi:[1,0]
	v_pk_mul_f32 v[2:3], v[2:3], v[62:63] op_sel_hi:[1,0]
	v_cndmask_b32_e64 v253, v253, v62, s[100:101]
	s_waitcnt vmcnt(4)
	v_pk_fma_f32 v[0:1], v[38:39], v[0:1], v[42:43]
	v_pk_fma_f32 v[2:3], v[40:41], v[2:3], v[44:45]
	global_load_dword v251, v[20:21], off
	v_cvt_pk_bf16_f32 v4, v0, v1
	v_cvt_pk_bf16_f32 v5, v2, v3
	v_mul_f32_e32 v0, 0x41000000, v0
	v_mul_f32_e32 v1, 0x41000000, v1
	v_cvt_pk_fp8_f32 v37, v0, v1
	v_mul_f32_e32 v2, 0x41000000, v2
	v_mul_f32_e32 v3, 0x41000000, v3
	global_store_dwordx2 v[32:33], v[4:5], off offset:-1024
	v_cvt_pk_fp8_f32 v37, v2, v3 op_sel:[0,0,1]
	v_pk_mul_f32 v[38:39], v[64:65], v[62:63] op_sel_hi:[1,0]
	v_pk_mul_f32 v[40:41], v[66:67], v[62:63] op_sel_hi:[1,0]
	v_pk_mul_f32 v[8:9], v[8:9], v[62:63] op_sel_hi:[1,0]
	global_store_dword v[34:35], v37, off offset:-512
	global_load_dwordx4 v[0:3], v[20:21], off offset:1024
	global_load_dwordx4 v[4:7], v[22:23], off offset:1024
	v_pk_mul_f32 v[10:11], v[10:11], v[62:63] op_sel_hi:[1,0]
	v_pk_mul_f32 v[64:65], v[12:13], v[62:63] op_sel_hi:[1,0]
	v_pk_mul_f32 v[62:63], v[14:15], v[62:63] op_sel_hi:[1,0]
	s_waitcnt vmcnt(5)
	v_mov_b64_e32 v[12:13], v[58:59]
	v_mov_b64_e32 v[14:15], v[60:61]
	s_waitcnt vmcnt(0)
	v_pk_fma_f32 v[0:1], v[0:1], v[38:39], v[4:5]
	v_pk_fma_f32 v[2:3], v[2:3], v[40:41], v[6:7]
	global_load_dword v251, v[20:21], off
	v_cvt_pk_bf16_f32 v4, v0, v1
	v_cvt_pk_bf16_f32 v5, v2, v3
	v_mul_f32_e32 v0, 0x41000000, v0
	v_mul_f32_e32 v1, 0x41000000, v1
	v_cvt_pk_fp8_f32 v17, v0, v1
	v_mul_f32_e32 v2, 0x41000000, v2
	v_mul_f32_e32 v3, 0x41000000, v3
	global_store_dwordx2 v[32:33], v[4:5], off offset:-512
	v_cvt_pk_fp8_f32 v17, v2, v3 op_sel:[0,0,1]
	global_store_dword v[34:35], v17, off offset:-256
	global_load_dwordx4 v[0:3], v[20:21], off offset:2048
	global_load_dwordx4 v[4:7], v[22:23], off offset:2048
	v_mov_b32_e32 v17, 0
	s_waitcnt vmcnt(0)
	v_pk_fma_f32 v[0:1], v[8:9], v[0:1], v[4:5]
	v_pk_fma_f32 v[2:3], v[10:11], v[2:3], v[6:7]
	global_load_dword v251, v[20:21], off
	v_cvt_pk_bf16_f32 v4, v0, v1
	v_cvt_pk_bf16_f32 v5, v2, v3
	v_mul_f32_e32 v0, 0x41000000, v0
	v_mul_f32_e32 v1, 0x41000000, v1
	v_cvt_pk_fp8_f32 v17, v0, v1
	v_mul_f32_e32 v2, 0x41000000, v2
	v_mul_f32_e32 v3, 0x41000000, v3
	global_store_dwordx2 v[32:33], v[4:5], off
	v_cvt_pk_fp8_f32 v17, v2, v3 op_sel:[0,0,1]
	v_mov_b64_e32 v[0:1], v[46:47]
	v_mov_b64_e32 v[2:3], v[48:49]
	v_mov_b64_e32 v[4:5], v[50:51]
	global_store_dword v[34:35], v17, off
	global_load_dwordx4 v[38:41], v[20:21], off offset:3072
	global_load_dwordx4 v[42:45], v[22:23], off offset:3072
	v_mov_b32_e32 v17, 0
	v_mov_b64_e32 v[6:7], v[52:53]
	v_mov_b64_e32 v[8:9], v[54:55]
	v_mov_b64_e32 v[10:11], v[56:57]
	s_waitcnt vmcnt(0)
	v_pk_fma_f32 v[38:39], v[64:65], v[38:39], v[42:43]
	s_nop 0
	v_mul_f32_e32 v37, 0x41000000, v38
	v_mul_f32_e32 v42, 0x41000000, v39
	v_cvt_pk_fp8_f32 v17, v37, v42
	v_pk_fma_f32 v[40:41], v[62:63], v[40:41], v[44:45]
	global_load_dword v251, v[20:21], off
	v_mul_f32_e32 v30, 0x41000000, v40
	v_mul_f32_e32 v31, 0x41000000, v41
	v_cvt_pk_fp8_f32 v17, v30, v31 op_sel:[0,0,1]
	v_cvt_pk_bf16_f32 v30, v38, v39
	v_cvt_pk_bf16_f32 v31, v40, v41
	global_store_dwordx2 v[32:33], v[30:31], off offset:512
	global_store_dword v[34:35], v17, off offset:256
	s_cbranch_scc1 .LBB0_1033
	s_mov_b64 s[54:55], 0
	s_barrier
	s_add_u32 s50, s96, s54
	s_addc_u32 s51, s97, s55
	s_add_u32 s3, s50, s58
	s_addc_u32 s16, s51, s59
	s_add_u32 s56, s3, 0x8000000
	s_addc_u32 s57, s16, 0
	s_add_u32 s52, s3, 0x28000000
	s_addc_u32 s53, s16, 0
	s_add_u32 s16, s50, 0x1600000
	s_addc_u32 s66, s51, 0
	s_add_u32 s3, s54, s46
	s_addc_u32 s59, s55, s47
	s_add_u32 s58, s96, s3
	s_addc_u32 s59, s97, s59
	s_mov_b32 s67, 0
	s_mov_b64 s[60:61], s[50:51]

.LBB0_1139:
	s_and_b32 s39, s41, 31
	v_or_b32_e32 v138, s39, v74
	s_and_b32 s18, s6, 0xf80
	s_lshr_b32 s11, s41, 5
	s_cmp_lg_u32 s39, 0
	s_cbranch_scc1 .Lvsw_skip_gb
	v_readlane_b32 s100, v255, 10
	v_readlane_b32 s101, v255, 11
	v_readlane_b32 s98, v255, 12
	v_readlane_b32 s99, v255, 13
	v_lshl_or_b32 v250, s11, 7, v34
	v_lshlrev_b32_e32 v250, 2, v250
	s_nop 4
	global_load_dwordx2 v[246:247], v250, s[100:101]
	global_load_dwordx2 v[248:249], v250, s[98:99]
	s_waitcnt vmcnt(0)
.Lvsw_skip_gb:
	v_readlane_b32 s100, v252, s39
	v_readlane_b32 s101, v253, s39
	v_ashrrev_i32_e32 v139, 31, v138
	v_lshl_add_u32 v173, s18, 1, v145
	s_lshl_b32 s18, s11, 7
	v_lshlrev_b64 v[138:139], 10, v[138:139]
	v_lshl_add_u64 v[138:139], v[138:139], 0, s[18:19]
	s_lshl_b32 s18, s11, 21
	s_waitcnt lgkmcnt(7)
	v_lshlrev_b32_sdwa v72, v141, v153 dst_sel:DWORD dst_unused:UNUSED_PAD src0_sel:DWORD src1_sel:WORD_0
	s_waitcnt vmcnt(7)
	v_cvt_pk_f32_fp8_e32 v[36:37], v28
	v_cvt_pk_f32_fp8_sdwa v[38:39], v28 src0_sel:WORD_1
	v_cvt_pk_f32_fp8_e32 v[40:41], v29
	v_cvt_pk_f32_fp8_sdwa v[28:29], v29 src0_sel:WORD_1
	v_cvt_pk_f32_fp8_e32 v[42:43], v30
	v_cvt_pk_f32_fp8_sdwa v[44:45], v30 src0_sel:WORD_1
	v_cvt_pk_f32_fp8_e32 v[48:49], v31
	v_cvt_pk_f32_fp8_sdwa v[50:51], v31 src0_sel:WORD_1
	v_lshl_add_u64 v[162:163], v[32:33], 0, s[18:19]
	s_waitcnt vmcnt(6)
	v_cvt_pk_f32_fp8_e32 v[30:31], v20
	v_cvt_pk_f32_fp8_sdwa v[46:47], v20 src0_sel:WORD_1
	v_cvt_pk_f32_fp8_e32 v[52:53], v21
	v_cvt_pk_f32_fp8_sdwa v[54:55], v21 src0_sel:WORD_1
	v_cvt_pk_f32_fp8_e32 v[58:59], v22
	v_cvt_pk_f32_fp8_sdwa v[60:61], v22 src0_sel:WORD_1
	v_cvt_pk_f32_fp8_e32 v[68:69], v23
	v_cvt_pk_f32_fp8_sdwa v[70:71], v23 src0_sel:WORD_1
	v_lshl_add_u32 v154, s39, 8, v77
	v_or_b32_e32 v138, v138, v34
	v_lshl_add_u64 v[156:157], v[162:163], 0, v[72:73]
	s_waitcnt lgkmcnt(6)
	v_lshlrev_b32_sdwa v72, v141, v146 dst_sel:DWORD dst_unused:UNUSED_PAD src0_sel:DWORD src1_sel:WORD_0
	s_waitcnt vmcnt(5)
	v_cvt_pk_f32_fp8_e32 v[20:21], v24
	v_cvt_pk_f32_fp8_sdwa v[22:23], v24 src0_sel:WORD_1
	v_cvt_pk_f32_fp8_e32 v[56:57], v25
	v_cvt_pk_f32_fp8_sdwa v[24:25], v25 src0_sel:WORD_1
	v_cvt_pk_f32_fp8_e32 v[62:63], v26
	v_cvt_pk_f32_fp8_sdwa v[64:65], v26 src0_sel:WORD_1
	v_cvt_pk_f32_fp8_e32 v[78:79], v27
	v_cvt_pk_f32_fp8_sdwa v[80:81], v27 src0_sel:WORD_1
	ds_read_u16 v175, v173
	ds_read_u16 v179, v173 offset:16
	ds_read_u16 v181, v173 offset:32
	ds_read_u16 v183, v173 offset:48
	ds_read_u16 v185, v173 offset:64
	ds_read_u16 v187, v173 offset:80
	ds_read_u16 v189, v173 offset:96
	ds_read_u16 v191, v173 offset:112
	ds_read_u16 v160, v154
	ds_read_u16 v161, v154 offset:16
	ds_read_u16 v169, v154 offset:32
	ds_read_u16 v174, v154 offset:48
	ds_read_u16 v180, v154 offset:64
	ds_read_u16 v182, v154 offset:80
	ds_read_u16 v184, v154 offset:96
	ds_read_u16 v186, v154 offset:112
	ds_read_u16 v153, v173 offset:128
	ds_read_u16 v188, v154 offset:128
	ds_read_u16 v190, v154 offset:144
	ds_read_u16 v192, v154 offset:160
	ds_read_u16 v193, v154 offset:176
	ds_read_u16 v195, v154 offset:192
	ds_read_u16 v197, v154 offset:208
	ds_read_u16 v199, v154 offset:224
	ds_read_u16 v201, v154 offset:240
	v_lshlrev_b64 v[154:155], 2, v[138:139]
	v_lshl_add_u64 v[138:139], v[138:139], 1, s[64:65]
	v_lshl_add_u64 v[158:159], v[162:163], 0, v[72:73]
	s_waitcnt lgkmcnt(14)
	v_lshlrev_b32_sdwa v72, v141, v151 dst_sel:DWORD dst_unused:UNUSED_PAD src0_sel:DWORD src1_sel:WORD_0
	s_waitcnt vmcnt(4)
	v_cvt_pk_f32_fp8_e32 v[26:27], v12
	v_cvt_pk_f32_fp8_sdwa v[66:67], v12 src0_sel:WORD_1
	v_cvt_pk_f32_fp8_e32 v[82:83], v13
	v_cvt_pk_f32_fp8_sdwa v[12:13], v13 src0_sel:WORD_1
	v_cvt_pk_f32_fp8_e32 v[86:87], v14
	v_cvt_pk_f32_fp8_sdwa v[88:89], v14 src0_sel:WORD_1
	v_cvt_pk_f32_fp8_e32 v[92:93], v15
	v_cvt_pk_f32_fp8_sdwa v[94:95], v15 src0_sel:WORD_1
	ds_read_u16 v146, v173 offset:144
	ds_read_u16 v151, v173 offset:160
	v_lshl_add_u64 v[166:167], s[62:63], 0, v[154:155]
	global_load_dword v203, v[138:139], off
	v_lshlrev_b32_e32 v168, 16, v160
	v_lshlrev_b32_e32 v170, 16, v161
	v_lshl_add_u64 v[138:139], s[60:61], 0, v[154:155]
	global_load_dwordx4 v[154:157], v[156:157], off
	s_nop 0
	global_load_dwordx4 v[158:161], v[158:159], off
	v_lshl_add_u64 v[204:205], v[162:163], 0, v[72:73]
	v_lshlrev_b32_sdwa v72, v141, v152 dst_sel:DWORD dst_unused:UNUSED_PAD src0_sel:DWORD src1_sel:WORD_0
	v_lshlrev_b32_e32 v172, 16, v169
	v_pk_fma_f32 v[36:37], v[36:37], v[168:169], 0 op_sel_hi:[1,0,0]
	v_pk_fma_f32 v[38:39], v[38:39], v[168:169], 0 op_sel_hi:[1,0,0]
	v_pk_fma_f32 v[40:41], v[40:41], v[168:169], 0 op_sel_hi:[1,0,0]
	v_pk_fma_f32 v[28:29], v[28:29], v[168:169], 0 op_sel_hi:[1,0,0]
	v_pk_fma_f32 v[42:43], v[42:43], v[168:169], 0 op_sel_hi:[1,0,0]
	v_pk_fma_f32 v[44:45], v[44:45], v[168:169], 0 op_sel_hi:[1,0,0]
	v_pk_fma_f32 v[48:49], v[48:49], v[168:169], 0 op_sel_hi:[1,0,0]
	v_pk_fma_f32 v[50:51], v[50:51], v[168:169], 0 op_sel_hi:[1,0,0]
	v_lshl_add_u64 v[168:169], v[162:163], 0, v[72:73]
	v_lshlrev_b32_sdwa v72, v141, v147 dst_sel:DWORD dst_unused:UNUSED_PAD src0_sel:DWORD src1_sel:WORD_0
	s_waitcnt vmcnt(6)
	v_cvt_pk_f32_fp8_e32 v[14:15], v16
	v_cvt_pk_f32_fp8_sdwa v[84:85], v16 src0_sel:WORD_1
	v_cvt_pk_f32_fp8_e32 v[90:91], v17
	v_cvt_pk_f32_fp8_sdwa v[16:17], v17 src0_sel:WORD_1
	v_cvt_pk_f32_fp8_e32 v[96:97], v18
	v_cvt_pk_f32_fp8_sdwa v[98:99], v18 src0_sel:WORD_1
	v_cvt_pk_f32_fp8_e32 v[100:101], v19
	v_cvt_pk_f32_fp8_sdwa v[18:19], v19 src0_sel:WORD_1
	ds_read_u16 v152, v173 offset:176
	ds_read_u16 v147, v173 offset:192
	global_load_dwordx2 v[166:167], v[166:167], off
	v_pk_fma_f32 v[30:31], v[30:31], v[170:171], v[36:37] op_sel_hi:[1,0,1]
	v_pk_fma_f32 v[46:47], v[46:47], v[170:171], v[38:39] op_sel_hi:[1,0,1]
	v_pk_fma_f32 v[52:53], v[52:53], v[170:171], v[40:41] op_sel_hi:[1,0,1]
	v_pk_fma_f32 v[28:29], v[54:55], v[170:171], v[28:29] op_sel_hi:[1,0,1]
	v_pk_fma_f32 v[54:55], v[58:59], v[170:171], v[42:43] op_sel_hi:[1,0,1]
	v_pk_fma_f32 v[44:45], v[60:61], v[170:171], v[44:45] op_sel_hi:[1,0,1]
	v_pk_fma_f32 v[48:49], v[68:69], v[170:171], v[48:49] op_sel_hi:[1,0,1]
	v_pk_fma_f32 v[50:51], v[70:71], v[170:171], v[50:51] op_sel_hi:[1,0,1]
	global_load_dwordx4 v[36:39], v[204:205], off
	global_load_dwordx4 v[40:43], v[168:169], off
	v_lshl_add_u64 v[58:59], v[162:163], 0, v[72:73]
	v_lshlrev_b32_sdwa v72, v141, v148 dst_sel:DWORD dst_unused:UNUSED_PAD src0_sel:DWORD src1_sel:WORD_0
	s_waitcnt lgkmcnt(14)
	v_lshlrev_b32_e32 v174, 16, v174
	v_pk_fma_f32 v[20:21], v[20:21], v[172:173], v[30:31] op_sel_hi:[1,0,1]
	v_pk_fma_f32 v[22:23], v[22:23], v[172:173], v[46:47] op_sel_hi:[1,0,1]
	v_pk_fma_f32 v[30:31], v[56:57], v[172:173], v[52:53] op_sel_hi:[1,0,1]
	v_pk_fma_f32 v[24:25], v[24:25], v[172:173], v[28:29] op_sel_hi:[1,0,1]
	v_pk_fma_f32 v[28:29], v[62:63], v[172:173], v[54:55] op_sel_hi:[1,0,1]
	v_pk_fma_f32 v[44:45], v[64:65], v[172:173], v[44:45] op_sel_hi:[1,0,1]
	v_pk_fma_f32 v[46:47], v[78:79], v[172:173], v[48:49] op_sel_hi:[1,0,1]
	v_pk_fma_f32 v[48:49], v[80:81], v[172:173], v[50:51] op_sel_hi:[1,0,1]
	v_lshl_add_u64 v[50:51], v[162:163], 0, v[72:73]
	ds_read_u16 v148, v173 offset:208
	v_lshlrev_b32_sdwa v72, v141, v149 dst_sel:DWORD dst_unused:UNUSED_PAD src0_sel:DWORD src1_sel:WORD_0
	ds_read_u16 v149, v173 offset:224
	v_pk_fma_f32 v[20:21], v[26:27], v[174:175], v[20:21] op_sel_hi:[1,0,1]
	v_pk_fma_f32 v[26:27], v[82:83], v[174:175], v[30:31] op_sel_hi:[1,0,1]
	v_pk_fma_f32 v[12:13], v[12:13], v[174:175], v[24:25] op_sel_hi:[1,0,1]
	v_pk_fma_f32 v[24:25], v[86:87], v[174:175], v[28:29] op_sel_hi:[1,0,1]
	v_pk_fma_f32 v[28:29], v[88:89], v[174:175], v[44:45] op_sel_hi:[1,0,1]
	v_pk_fma_f32 v[30:31], v[92:93], v[174:175], v[46:47] op_sel_hi:[1,0,1]
	v_pk_fma_f32 v[52:53], v[94:95], v[174:175], v[48:49] op_sel_hi:[1,0,1]
	global_load_dwordx4 v[44:47], v[58:59], off
	s_nop 0
	global_load_dwordx4 v[48:51], v[50:51], off
	v_lshlrev_b32_e32 v180, 16, v180
	v_lshl_add_u64 v[54:55], v[162:163], 0, v[72:73]
	v_lshlrev_b32_sdwa v72, v141, v150 dst_sel:DWORD dst_unused:UNUSED_PAD src0_sel:DWORD src1_sel:WORD_0
	ds_read_u16 v150, v173 offset:240
	v_pk_fma_f32 v[12:13], v[16:17], v[180:181], v[12:13] op_sel_hi:[1,0,1]
	v_pk_fma_f32 v[16:17], v[96:97], v[180:181], v[24:25] op_sel_hi:[1,0,1]
	v_pk_fma_f32 v[24:25], v[98:99], v[180:181], v[28:29] op_sel_hi:[1,0,1]
	v_pk_fma_f32 v[18:19], v[18:19], v[180:181], v[52:53] op_sel_hi:[1,0,1]
	v_lshl_add_u64 v[28:29], v[162:163], 0, v[72:73]
	global_load_dwordx4 v[52:55], v[54:55], off
	s_nop 0
	global_load_dwordx4 v[56:59], v[28:29], off
	s_waitcnt vmcnt(12)
	v_cvt_pk_f32_fp8_e32 v[102:103], v4
	v_cvt_pk_f32_fp8_sdwa v[104:105], v4 src0_sel:WORD_1
	v_cvt_pk_f32_fp8_e32 v[106:107], v5
	v_cvt_pk_f32_fp8_sdwa v[4:5], v5 src0_sel:WORD_1
	v_cvt_pk_f32_fp8_e32 v[108:109], v6
	v_cvt_pk_f32_fp8_sdwa v[110:111], v6 src0_sel:WORD_1
	v_cvt_pk_f32_fp8_e32 v[114:115], v7
	v_cvt_pk_f32_fp8_sdwa v[116:117], v7 src0_sel:WORD_1
	s_waitcnt vmcnt(11)
	v_cvt_pk_f32_fp8_e32 v[6:7], v8
	v_cvt_pk_f32_fp8_sdwa v[112:113], v8 src0_sel:WORD_1
	v_cvt_pk_f32_fp8_e32 v[118:119], v9
	v_cvt_pk_f32_fp8_sdwa v[8:9], v9 src0_sel:WORD_1
	v_cvt_pk_f32_fp8_e32 v[120:121], v10
	v_cvt_pk_f32_fp8_sdwa v[122:123], v10 src0_sel:WORD_1
	v_cvt_pk_f32_fp8_e32 v[124:125], v11
	v_cvt_pk_f32_fp8_sdwa v[10:11], v11 src0_sel:WORD_1
	s_waitcnt vmcnt(10)
	v_cvt_pk_f32_fp8_e32 v[126:127], v0
	v_cvt_pk_f32_fp8_sdwa v[128:129], v0 src0_sel:WORD_1
	v_cvt_pk_f32_fp8_e32 v[130:131], v1
	v_cvt_pk_f32_fp8_sdwa v[0:1], v1 src0_sel:WORD_1
	s_and_b32 s18, s3, 0xe00000
	v_pk_fma_f32 v[22:23], v[66:67], v[174:175], v[22:23] op_sel_hi:[1,0,1]
	v_cvt_pk_f32_fp8_e32 v[132:133], v2
	v_cvt_pk_f32_fp8_sdwa v[134:135], v2 src0_sel:WORD_1
	v_cvt_pk_f32_fp8_e32 v[136:137], v3
	v_cvt_pk_f32_fp8_sdwa v[2:3], v3 src0_sel:WORD_1
	v_lshl_add_u64 v[164:165], v[32:33], 0, s[18:19]
	v_lshlrev_b32_e32 v182, 16, v182
	v_pk_fma_f32 v[14:15], v[14:15], v[180:181], v[20:21] op_sel_hi:[1,0,1]
	v_pk_fma_f32 v[20:21], v[84:85], v[180:181], v[22:23] op_sel_hi:[1,0,1]
	v_pk_fma_f32 v[22:23], v[90:91], v[180:181], v[26:27] op_sel_hi:[1,0,1]
	v_pk_fma_f32 v[26:27], v[100:101], v[180:181], v[30:31] op_sel_hi:[1,0,1]
	v_lshlrev_b32_e32 v72, 7, v175
	v_lshlrev_b32_e32 v184, 16, v184
	v_pk_fma_f32 v[4:5], v[4:5], v[182:183], v[12:13] op_sel_hi:[1,0,1]
	v_pk_fma_f32 v[12:13], v[108:109], v[182:183], v[16:17] op_sel_hi:[1,0,1]
	v_pk_fma_f32 v[16:17], v[110:111], v[182:183], v[24:25] op_sel_hi:[1,0,1]
	v_pk_fma_f32 v[24:25], v[114:115], v[182:183], v[26:27] op_sel_hi:[1,0,1]
	v_pk_fma_f32 v[18:19], v[116:117], v[182:183], v[18:19] op_sel_hi:[1,0,1]
	v_lshl_add_u64 v[26:27], v[164:165], 0, v[72:73]
	v_lshlrev_b32_e32 v72, 7, v179
	s_waitcnt lgkmcnt(14)
	v_lshlrev_b32_e32 v186, 16, v186
	v_pk_fma_f32 v[4:5], v[8:9], v[184:185], v[4:5] op_sel_hi:[1,0,1]
	v_pk_fma_f32 v[10:11], v[10:11], v[184:185], v[18:19] op_sel_hi:[1,0,1]
	v_lshl_add_u64 v[18:19], v[164:165], 0, v[72:73]
	v_lshlrev_b32_e32 v72, 7, v181
	v_pk_fma_f32 v[14:15], v[102:103], v[182:183], v[14:15] op_sel_hi:[1,0,1]
	v_pk_fma_f32 v[20:21], v[104:105], v[182:183], v[20:21] op_sel_hi:[1,0,1]
	v_pk_fma_f32 v[22:23], v[106:107], v[182:183], v[22:23] op_sel_hi:[1,0,1]
	v_pk_fma_f32 v[66:67], v[0:1], v[186:187], v[4:5] op_sel_hi:[1,0,1]
	v_lshl_add_u64 v[0:1], v[164:165], 0, v[72:73]
	v_lshlrev_b32_e32 v72, 7, v183
	v_pk_fma_f32 v[6:7], v[6:7], v[184:185], v[14:15] op_sel_hi:[1,0,1]
	v_pk_fma_f32 v[14:15], v[112:113], v[184:185], v[20:21] op_sel_hi:[1,0,1]
	v_pk_fma_f32 v[20:21], v[118:119], v[184:185], v[22:23] op_sel_hi:[1,0,1]
	v_pk_fma_f32 v[8:9], v[120:121], v[184:185], v[12:13] op_sel_hi:[1,0,1]
	v_pk_fma_f32 v[12:13], v[122:123], v[184:185], v[16:17] op_sel_hi:[1,0,1]
	v_pk_fma_f32 v[80:81], v[2:3], v[186:187], v[10:11] op_sel_hi:[1,0,1]
	v_lshl_add_u64 v[2:3], v[164:165], 0, v[72:73]
	v_lshlrev_b32_e32 v72, 7, v185
	v_pk_fma_f32 v[16:17], v[124:125], v[184:185], v[24:25] op_sel_hi:[1,0,1]
	v_pk_fma_f32 v[62:63], v[128:129], v[186:187], v[14:15] op_sel_hi:[1,0,1]
	v_pk_fma_f32 v[64:65], v[130:131], v[186:187], v[20:21] op_sel_hi:[1,0,1]
	v_pk_fma_f32 v[70:71], v[134:135], v[186:187], v[12:13] op_sel_hi:[1,0,1]
	global_load_dwordx4 v[28:31], v[26:27], off
	global_load_dwordx4 v[20:23], v[18:19], off
	s_nop 0
	global_load_dwordx4 v[24:27], v[0:1], off
	global_load_dwordx4 v[12:15], v[2:3], off
	v_lshl_add_u64 v[0:1], v[164:165], 0, v[72:73]
	v_lshlrev_b32_e32 v72, 7, v187
	v_lshl_add_u64 v[2:3], v[164:165], 0, v[72:73]
	v_lshlrev_b32_e32 v72, 7, v189
	v_pk_fma_f32 v[60:61], v[126:127], v[186:187], v[6:7] op_sel_hi:[1,0,1]
	v_pk_fma_f32 v[78:79], v[136:137], v[186:187], v[16:17] op_sel_hi:[1,0,1]
	global_load_dwordx4 v[16:19], v[0:1], off
	global_load_dwordx4 v[4:7], v[2:3], off
	v_lshl_add_u64 v[0:1], v[164:165], 0, v[72:73]
	v_lshlrev_b32_e32 v72, 7, v191
	v_lshl_add_u64 v[2:3], v[164:165], 0, v[72:73]
	v_pk_fma_f32 v[68:69], v[132:133], v[186:187], v[8:9] op_sel_hi:[1,0,1]
	global_load_dwordx4 v[8:11], v[0:1], off
	s_nop 0
	global_load_dwordx4 v[0:3], v[2:3], off
	s_waitcnt vmcnt(16)
	v_cvt_pk_f32_fp8_e32 v[82:83], v154
	v_cvt_pk_f32_fp8_sdwa v[84:85], v154 src0_sel:WORD_1
	v_cvt_pk_f32_fp8_e32 v[86:87], v155
	v_cvt_pk_f32_fp8_sdwa v[88:89], v155 src0_sel:WORD_1
	v_cvt_pk_f32_fp8_e32 v[90:91], v156
	v_cvt_pk_f32_fp8_sdwa v[92:93], v156 src0_sel:WORD_1
	v_cvt_pk_f32_fp8_e32 v[94:95], v157
	v_cvt_pk_f32_fp8_sdwa v[96:97], v157 src0_sel:WORD_1
	s_waitcnt vmcnt(15)
	v_cvt_pk_f32_fp8_e32 v[100:101], v158
	v_cvt_pk_f32_fp8_sdwa v[102:103], v158 src0_sel:WORD_1
	v_cvt_pk_f32_fp8_e32 v[104:105], v159
	v_cvt_pk_f32_fp8_sdwa v[106:107], v159 src0_sel:WORD_1
	v_cvt_pk_f32_fp8_e32 v[108:109], v160
	v_cvt_pk_f32_fp8_sdwa v[110:111], v160 src0_sel:WORD_1
	v_cvt_pk_f32_fp8_e32 v[112:113], v161
	v_cvt_pk_f32_fp8_sdwa v[114:115], v161 src0_sel:WORD_1
	s_waitcnt vmcnt(13)
	v_cvt_pk_f32_fp8_e32 v[116:117], v36
	v_cvt_pk_f32_fp8_sdwa v[118:119], v36 src0_sel:WORD_1
	v_cvt_pk_f32_fp8_e32 v[120:121], v37
	v_cvt_pk_f32_fp8_sdwa v[36:37], v37 src0_sel:WORD_1
	v_cvt_pk_f32_fp8_e32 v[122:123], v38
	v_cvt_pk_f32_fp8_sdwa v[124:125], v38 src0_sel:WORD_1
	v_cvt_pk_f32_fp8_e32 v[126:127], v39
	v_cvt_pk_f32_fp8_sdwa v[38:39], v39 src0_sel:WORD_1
	v_lshlrev_b32_e32 v188, 16, v188
	s_waitcnt vmcnt(12)
	v_cvt_pk_f32_fp8_e32 v[128:129], v40
	v_cvt_pk_f32_fp8_sdwa v[130:131], v40 src0_sel:WORD_1
	v_cvt_pk_f32_fp8_e32 v[132:133], v41
	v_cvt_pk_f32_fp8_sdwa v[40:41], v41 src0_sel:WORD_1
	v_cvt_pk_f32_fp8_e32 v[134:135], v42
	v_cvt_pk_f32_fp8_sdwa v[136:137], v42 src0_sel:WORD_1
	v_cvt_pk_f32_fp8_e32 v[154:155], v43
	v_cvt_pk_f32_fp8_sdwa v[42:43], v43 src0_sel:WORD_1
	s_waitcnt lgkmcnt(13)
	v_lshlrev_b32_e32 v190, 16, v190
	v_pk_fma_f32 v[60:61], v[82:83], v[188:189], v[60:61] op_sel_hi:[1,0,1]
	v_pk_fma_f32 v[62:63], v[84:85], v[188:189], v[62:63] op_sel_hi:[1,0,1]
	v_pk_fma_f32 v[64:65], v[86:87], v[188:189], v[64:65] op_sel_hi:[1,0,1]
	v_pk_fma_f32 v[66:67], v[88:89], v[188:189], v[66:67] op_sel_hi:[1,0,1]
	v_pk_fma_f32 v[68:69], v[90:91], v[188:189], v[68:69] op_sel_hi:[1,0,1]
	v_pk_fma_f32 v[70:71], v[92:93], v[188:189], v[70:71] op_sel_hi:[1,0,1]
	v_pk_fma_f32 v[78:79], v[94:95], v[188:189], v[78:79] op_sel_hi:[1,0,1]
	v_pk_fma_f32 v[80:81], v[96:97], v[188:189], v[80:81] op_sel_hi:[1,0,1]
	s_waitcnt vmcnt(11)
	v_cvt_pk_f32_fp8_e32 v[82:83], v44
	v_cvt_pk_f32_fp8_sdwa v[84:85], v44 src0_sel:WORD_1
	v_cvt_pk_f32_fp8_e32 v[86:87], v45
	v_cvt_pk_f32_fp8_sdwa v[44:45], v45 src0_sel:WORD_1
	v_cvt_pk_f32_fp8_e32 v[88:89], v46
	v_cvt_pk_f32_fp8_sdwa v[90:91], v46 src0_sel:WORD_1
	v_cvt_pk_f32_fp8_e32 v[92:93], v47
	v_cvt_pk_f32_fp8_sdwa v[46:47], v47 src0_sel:WORD_1
	s_waitcnt lgkmcnt(12)
	v_lshlrev_b32_e32 v192, 16, v192
	v_pk_fma_f32 v[60:61], v[100:101], v[190:191], v[60:61] op_sel_hi:[1,0,1]
	v_pk_fma_f32 v[62:63], v[102:103], v[190:191], v[62:63] op_sel_hi:[1,0,1]
	v_pk_fma_f32 v[64:65], v[104:105], v[190:191], v[64:65] op_sel_hi:[1,0,1]
	v_pk_fma_f32 v[66:67], v[106:107], v[190:191], v[66:67] op_sel_hi:[1,0,1]
	v_pk_fma_f32 v[68:69], v[108:109], v[190:191], v[68:69] op_sel_hi:[1,0,1]
	v_pk_fma_f32 v[70:71], v[110:111], v[190:191], v[70:71] op_sel_hi:[1,0,1]
	v_pk_fma_f32 v[78:79], v[112:113], v[190:191], v[78:79] op_sel_hi:[1,0,1]
	v_pk_fma_f32 v[80:81], v[114:115], v[190:191], v[80:81] op_sel_hi:[1,0,1]
	s_waitcnt vmcnt(10)
	v_cvt_pk_f32_fp8_e32 v[94:95], v48
	v_cvt_pk_f32_fp8_sdwa v[96:97], v48 src0_sel:WORD_1
	v_cvt_pk_f32_fp8_e32 v[100:101], v49
	v_cvt_pk_f32_fp8_sdwa v[48:49], v49 src0_sel:WORD_1
	v_cvt_pk_f32_fp8_e32 v[102:103], v50
	v_cvt_pk_f32_fp8_sdwa v[104:105], v50 src0_sel:WORD_1
	v_cvt_pk_f32_fp8_e32 v[106:107], v51
	v_cvt_pk_f32_fp8_sdwa v[50:51], v51 src0_sel:WORD_1
	s_waitcnt lgkmcnt(11)
	v_lshlrev_b32_e32 v194, 16, v193
	v_pk_fma_f32 v[60:61], v[116:117], v[192:193], v[60:61] op_sel_hi:[1,0,1]
	v_pk_fma_f32 v[62:63], v[118:119], v[192:193], v[62:63] op_sel_hi:[1,0,1]
	v_pk_fma_f32 v[64:65], v[120:121], v[192:193], v[64:65] op_sel_hi:[1,0,1]
	v_pk_fma_f32 v[36:37], v[36:37], v[192:193], v[66:67] op_sel_hi:[1,0,1]
	v_pk_fma_f32 v[66:67], v[122:123], v[192:193], v[68:69] op_sel_hi:[1,0,1]
	v_pk_fma_f32 v[68:69], v[124:125], v[192:193], v[70:71] op_sel_hi:[1,0,1]
	v_pk_fma_f32 v[70:71], v[126:127], v[192:193], v[78:79] op_sel_hi:[1,0,1]
	v_pk_fma_f32 v[38:39], v[38:39], v[192:193], v[80:81] op_sel_hi:[1,0,1]
	s_waitcnt vmcnt(9)
	v_cvt_pk_f32_fp8_e32 v[78:79], v52
	v_cvt_pk_f32_fp8_sdwa v[80:81], v52 src0_sel:WORD_1
	v_cvt_pk_f32_fp8_e32 v[108:109], v53
	v_cvt_pk_f32_fp8_sdwa v[52:53], v53 src0_sel:WORD_1
	v_cvt_pk_f32_fp8_e32 v[110:111], v54
	v_cvt_pk_f32_fp8_sdwa v[112:113], v54 src0_sel:WORD_1
	v_cvt_pk_f32_fp8_e32 v[114:115], v55
	v_cvt_pk_f32_fp8_sdwa v[54:55], v55 src0_sel:WORD_1
	s_waitcnt lgkmcnt(10)
	v_lshlrev_b32_e32 v196, 16, v195
	v_pk_fma_f32 v[60:61], v[128:129], v[194:195], v[60:61] op_sel_hi:[1,0,1]
	v_pk_fma_f32 v[62:63], v[130:131], v[194:195], v[62:63] op_sel_hi:[1,0,1]
	v_pk_fma_f32 v[64:65], v[132:133], v[194:195], v[64:65] op_sel_hi:[1,0,1]
	v_pk_fma_f32 v[36:37], v[40:41], v[194:195], v[36:37] op_sel_hi:[1,0,1]
	v_pk_fma_f32 v[40:41], v[134:135], v[194:195], v[66:67] op_sel_hi:[1,0,1]
	v_pk_fma_f32 v[66:67], v[136:137], v[194:195], v[68:69] op_sel_hi:[1,0,1]
	v_pk_fma_f32 v[68:69], v[154:155], v[194:195], v[70:71] op_sel_hi:[1,0,1]
	v_pk_fma_f32 v[38:39], v[42:43], v[194:195], v[38:39] op_sel_hi:[1,0,1]
	s_waitcnt vmcnt(8)
	v_cvt_pk_f32_fp8_e32 v[42:43], v56
	v_cvt_pk_f32_fp8_sdwa v[70:71], v56 src0_sel:WORD_1
	v_cvt_pk_f32_fp8_e32 v[116:117], v57
	v_cvt_pk_f32_fp8_sdwa v[56:57], v57 src0_sel:WORD_1
	v_cvt_pk_f32_fp8_e32 v[118:119], v58
	v_cvt_pk_f32_fp8_sdwa v[120:121], v58 src0_sel:WORD_1
	v_cvt_pk_f32_fp8_e32 v[122:123], v59
	v_cvt_pk_f32_fp8_sdwa v[58:59], v59 src0_sel:WORD_1
	s_waitcnt lgkmcnt(9)
	v_lshlrev_b32_e32 v198, 16, v197
	v_pk_fma_f32 v[60:61], v[82:83], v[196:197], v[60:61] op_sel_hi:[1,0,1]
	v_pk_fma_f32 v[62:63], v[84:85], v[196:197], v[62:63] op_sel_hi:[1,0,1]
	v_pk_fma_f32 v[64:65], v[86:87], v[196:197], v[64:65] op_sel_hi:[1,0,1]
	v_pk_fma_f32 v[36:37], v[44:45], v[196:197], v[36:37] op_sel_hi:[1,0,1]
	v_pk_fma_f32 v[40:41], v[88:89], v[196:197], v[40:41] op_sel_hi:[1,0,1]
	v_pk_fma_f32 v[44:45], v[90:91], v[196:197], v[66:67] op_sel_hi:[1,0,1]
	v_pk_fma_f32 v[66:67], v[92:93], v[196:197], v[68:69] op_sel_hi:[1,0,1]
	v_pk_fma_f32 v[38:39], v[46:47], v[196:197], v[38:39] op_sel_hi:[1,0,1]
	s_waitcnt lgkmcnt(8)
	v_lshlrev_b32_e32 v200, 16, v199
	v_pk_fma_f32 v[46:47], v[94:95], v[198:199], v[60:61] op_sel_hi:[1,0,1]
	v_pk_fma_f32 v[60:61], v[96:97], v[198:199], v[62:63] op_sel_hi:[1,0,1]
	v_pk_fma_f32 v[62:63], v[100:101], v[198:199], v[64:65] op_sel_hi:[1,0,1]
	v_pk_fma_f32 v[36:37], v[48:49], v[198:199], v[36:37] op_sel_hi:[1,0,1]
	v_pk_fma_f32 v[40:41], v[102:103], v[198:199], v[40:41] op_sel_hi:[1,0,1]
	v_pk_fma_f32 v[44:45], v[104:105], v[198:199], v[44:45] op_sel_hi:[1,0,1]
	v_pk_fma_f32 v[48:49], v[106:107], v[198:199], v[66:67] op_sel_hi:[1,0,1]
	v_pk_fma_f32 v[38:39], v[50:51], v[198:199], v[38:39] op_sel_hi:[1,0,1]
	s_waitcnt lgkmcnt(7)
	v_lshlrev_b32_e32 v202, 16, v201
	v_pk_fma_f32 v[46:47], v[78:79], v[200:201], v[46:47] op_sel_hi:[1,0,1]
	v_pk_fma_f32 v[50:51], v[80:81], v[200:201], v[60:61] op_sel_hi:[1,0,1]
	v_pk_fma_f32 v[60:61], v[108:109], v[200:201], v[62:63] op_sel_hi:[1,0,1]
	v_pk_fma_f32 v[36:37], v[52:53], v[200:201], v[36:37] op_sel_hi:[1,0,1]
	v_pk_fma_f32 v[40:41], v[110:111], v[200:201], v[40:41] op_sel_hi:[1,0,1]
	v_pk_fma_f32 v[44:45], v[112:113], v[200:201], v[44:45] op_sel_hi:[1,0,1]
	v_pk_fma_f32 v[48:49], v[114:115], v[200:201], v[48:49] op_sel_hi:[1,0,1]
	v_pk_fma_f32 v[38:39], v[54:55], v[200:201], v[38:39] op_sel_hi:[1,0,1]
	v_pk_fma_f32 v[42:43], v[42:43], v[202:203], v[46:47] op_sel_hi:[1,0,1]
	v_pk_fma_f32 v[46:47], v[70:71], v[202:203], v[50:51] op_sel_hi:[1,0,1]
	v_pk_fma_f32 v[50:51], v[116:117], v[202:203], v[60:61] op_sel_hi:[1,0,1]
	v_pk_fma_f32 v[36:37], v[56:57], v[202:203], v[36:37] op_sel_hi:[1,0,1]
	v_pk_fma_f32 v[40:41], v[118:119], v[202:203], v[40:41] op_sel_hi:[1,0,1]
	v_pk_fma_f32 v[44:45], v[120:121], v[202:203], v[44:45] op_sel_hi:[1,0,1]
	v_pk_fma_f32 v[48:49], v[122:123], v[202:203], v[48:49] op_sel_hi:[1,0,1]
	v_pk_fma_f32 v[38:39], v[58:59], v[202:203], v[38:39] op_sel_hi:[1,0,1]
	v_cndmask_b32_e64 v52, v42, v40, s[4:5]
	v_cndmask_b32_e64 v53, v43, v41, s[4:5]
	v_cndmask_b32_e64 v41, v41, v43, s[4:5]
	v_cndmask_b32_e64 v40, v40, v42, s[4:5]
	v_cndmask_b32_e64 v54, v46, v44, s[4:5]
	v_cndmask_b32_e64 v55, v47, v45, s[4:5]
	v_cndmask_b32_e64 v43, v45, v47, s[4:5]
	v_cndmask_b32_e64 v42, v44, v46, s[4:5]
	v_cndmask_b32_e64 v56, v50, v48, s[4:5]
	v_cndmask_b32_e64 v57, v51, v49, s[4:5]
	v_cndmask_b32_e64 v45, v49, v51, s[4:5]
	v_cndmask_b32_e64 v44, v48, v50, s[4:5]
	v_cndmask_b32_e64 v50, v36, v38, s[4:5]
	v_cndmask_b32_e64 v51, v37, v39, s[4:5]
	v_cndmask_b32_e64 v37, v39, v37, s[4:5]
	v_cndmask_b32_e64 v36, v38, v36, s[4:5]
	ds_bpermute_b32 v38, v35, v52
	ds_bpermute_b32 v39, v35, v53
	ds_bpermute_b32 v46, v35, v54
	ds_bpermute_b32 v47, v35, v55
	ds_bpermute_b32 v48, v35, v56
	ds_bpermute_b32 v49, v35, v57
	ds_bpermute_b32 v50, v35, v50
	ds_bpermute_b32 v51, v35, v51
	s_waitcnt lgkmcnt(6)
	v_pk_add_f32 v[38:39], v[40:41], v[38:39]
	s_waitcnt lgkmcnt(4)
	v_pk_add_f32 v[40:41], v[42:43], v[46:47]
	s_waitcnt lgkmcnt(2)
	v_pk_add_f32 v[42:43], v[44:45], v[48:49]
	v_lshlrev_b32_e32 v98, 16, v203
	s_waitcnt lgkmcnt(0)
	v_pk_add_f32 v[36:37], v[36:37], v[50:51]
	v_cndmask_b32_e32 v44, v38, v42, vcc
	v_cndmask_b32_e32 v45, v39, v43, vcc
	v_cndmask_b32_e32 v39, v43, v39, vcc
	v_cndmask_b32_e32 v38, v42, v38, vcc
	v_cndmask_b32_e32 v42, v40, v36, vcc
	v_cndmask_b32_e32 v43, v41, v37, vcc
	v_cndmask_b32_e32 v37, v37, v41, vcc
	v_cndmask_b32_e32 v36, v36, v40, vcc
	ds_bpermute_b32 v40, v144, v44
	ds_bpermute_b32 v41, v144, v45
	ds_bpermute_b32 v42, v144, v42
	ds_bpermute_b32 v43, v144, v43
	v_and_b32_e32 v99, 0xffff0000, v203
	s_add_i32 s7, s41, 1
	s_waitcnt lgkmcnt(2)
	v_pk_add_f32 v[38:39], v[38:39], v[40:41]
	s_addk_i32 s6, 0x80
	s_waitcnt lgkmcnt(0)
	v_pk_add_f32 v[36:37], v[36:37], v[42:43]
	s_add_i32 s3, s3, 0x10000
	v_cndmask_b32_e64 v40, v38, v36, s[0:1]
	v_cndmask_b32_e64 v41, v39, v37, s[0:1]
	v_cndmask_b32_e64 v37, v37, v39, s[0:1]
	v_cndmask_b32_e64 v36, v36, v38, s[0:1]
	v_mov_b32_dpp v38, v40 row_ror:8 row_mask:0xf bank_mask:0xf bound_ctrl:1
	v_mov_b32_dpp v39, v41 row_ror:8 row_mask:0xf bank_mask:0xf bound_ctrl:1
	v_pk_add_f32 v[166:167], v[166:167], s[100:101] op_sel_hi:[1,0] neg_lo:[0,1] neg_hi:[0,1]
	s_nop 0
	v_pk_mul_f32 v[166:167], v[166:167], s[100:101] op_sel:[0,1]
	s_nop 0
	v_pk_fma_f32 v[166:167], v[246:247], v[166:167], v[248:249]
	s_nop 0
	v_pk_fma_f32 v[98:99], v[166:167], s[58:59], v[98:99] op_sel_hi:[1,0,1]
	v_pk_add_f32 v[36:37], v[36:37], v[38:39]
	s_mov_b32 s41, s7
	s_cmpk_eq_i32 s7, 0x100
	v_pk_add_f32 v[36:37], v[98:99], v[36:37]
	global_store_dwordx2 v[138:139], v[36:37], off
	s_cbranch_scc0 .LBB0_1139
	s_waitcnt vmcnt(1)
	v_lshlrev_b64 v[0:1], 12, v[74:75]
	v_lshl_add_u64 v[0:1], s[60:61], 0, v[0:1]
	v_mov_b32_e32 v77, v73
	v_lshl_add_u64 v[12:13], v[0:1], 0, v[76:77]
	s_barrier
	global_load_dwordx4 v[0:3], v[12:13], off
	global_load_dwordx4 v[4:7], v[12:13], off offset:1024
	global_load_dwordx4 v[8:11], v[12:13], off offset:2048
	s_nop 0
	global_load_dwordx4 v[12:15], v[12:13], off offset:3072
	v_lshl_add_u64 v[16:17], s[60:61], 0, v[76:77]
	v_lshl_add_u64 v[18:19], s[90:91], 0, v[76:77]
	v_lshl_add_u64 v[20:21], s[68:69], 0, v[76:77]
	v_lshl_add_u64 v[22:23], s[70:71], 0, v[76:77]
	v_add_u32_e32 v24, s10, v74
	s_mov_b32 s0, 0
